# kvnorm pass: next row's load in flight while the current row is reduced; 64-lane sum by DPP tree + readlane instead of six ds_bpermute round trips
# speedup vs baseline: 1.0856x; 1.0026x over previous
; DI void kvnorm_pass(const float* raw, const float* g1, u16* ckv) {
;     ...
;   for (int row = blockIdx.x * 8 + w; row < M; row += gridDim.x * 8) {
;     f32x4 v = *(const f32x4*)(raw + (size_t)row * 256 + lane * 4);
.Lkv_a:
	s_lshl_b64 s[0:1], s[8:9], 9
	v_lshl_add_u64 v[26:27], v[6:7], 0, s[0:1]
	s_add_i32 s8, s8, s10
	s_ashr_i32 s9, s8, 31
	s_cmpk_gt_i32 s8, 0x407f
	s_cbranch_scc1 .Lkv_a_last
	s_lshl_b64 s[0:1], s[8:9], 10
	v_lshl_add_u64 v[22:23], v[4:5], 0, s[0:1]
	global_load_dwordx4 v[22:25], v[22:23], off
	s_waitcnt vmcnt(1)
	s_branch .Lkv_a_go

; DI float shx(float v, int mask, int lane) { return __int_as_float(__builtin_amdgcn_ds_bpermute((lane ^ mask) << 2, __float_as_int(v))); }
; DI void kvnorm_pass(const float* raw, const float* g1, u16* ckv) {
;     ...
;     f32x4 v = *(const f32x4*)(raw + (size_t)row * 256 + lane * 4);
;     float s = v[0] * v[0] + v[1] * v[1] + v[2] * v[2] + v[3] * v[3];
; #pragma unroll
;     for (int o_ = 32; o_ >= 1; o_ >>= 1) s += shx(s, o_, lane);
;     const float r = rsqrtf(s * (1.f / 256.f) + 1e-6f);
;     v = v * g * r;
;     *(u32x2*)(ckv + (size_t)row * 256 + lane * 4) = MK2(pack2(v[0], v[1]), pack2(v[2], v[3]));
;   }
.Lkv_a_go:
	v_pk_mul_f32 v[20:21], v[14:15], v[14:15]
	v_pk_mul_f32 v[18:19], v[16:17], v[16:17]
	v_add_f32_e32 v20, v20, v21
	v_add_f32_e32 v18, v18, v20
	v_add_f32_e32 v18, v19, v18
	v_pk_mul_f32 v[16:17], v[2:3], v[16:17]
	v_pk_mul_f32 v[14:15], v[0:1], v[14:15]
	s_nop 1
	v_add_f32_dpp v18, v18, v18 quad_perm:[1,0,3,2] row_mask:0xf bank_mask:0xf
	s_nop 1
	v_add_f32_dpp v18, v18, v18 quad_perm:[2,3,0,1] row_mask:0xf bank_mask:0xf
	s_nop 1
	v_add_f32_dpp v18, v18, v18 row_half_mirror row_mask:0xf bank_mask:0xf
	s_nop 1
	v_add_f32_dpp v18, v18, v18 row_mirror row_mask:0xf bank_mask:0xf
	s_nop 1
	v_add_f32_dpp v18, v18, v18 row_bcast:15 row_mask:0xa bank_mask:0xf
	s_nop 1
	v_add_f32_dpp v18, v18, v18 row_bcast:31 row_mask:0xc bank_mask:0xf
	s_nop 1
	v_readlane_b32 s0, v18, 63
	s_nop 1
	v_mov_b32_e32 v18, s0
	v_fmamk_f32 v18, v18, 0x3b800000, v211
	v_cmp_gt_f32_e32 vcc, s33, v18
	v_mul_f32_e32 v19, 0x4b800000, v18
	s_nop 0
	v_cndmask_b32_e32 v18, v18, v19, vcc
	v_rsq_f32_e32 v18, v18
	s_nop 0
	v_mul_f32_e32 v19, 0x45800000, v18
	v_cndmask_b32_e32 v18, v18, v19, vcc
	v_pk_mul_f32 v[16:17], v[16:17], v[18:19] op_sel_hi:[1,0]
	v_pk_mul_f32 v[14:15], v[14:15], v[18:19] op_sel_hi:[1,0]
	s_nop 0
	v_cvt_pk_bf16_f32 v14, v14, v15
	v_cvt_pk_bf16_f32 v15, v16, v17
	global_store_dwordx2 v[26:27], v[14:15], off
	s_cmpk_gt_i32 s8, 0x407f
	s_cbranch_scc1 .LBB0_86
.Lkv_b:
	s_lshl_b64 s[0:1], s[8:9], 9
	v_lshl_add_u64 v[26:27], v[6:7], 0, s[0:1]
	s_add_i32 s8, s8, s10
	s_ashr_i32 s9, s8, 31
	s_cmpk_gt_i32 s8, 0x407f
	s_cbranch_scc1 .Lkv_b_last
	s_lshl_b64 s[0:1], s[8:9], 10
	v_lshl_add_u64 v[14:15], v[4:5], 0, s[0:1]
	global_load_dwordx4 v[14:17], v[14:15], off
	s_waitcnt vmcnt(1)
	s_branch .Lkv_b_go

; DI float shx(float v, int mask, int lane) { return __int_as_float(__builtin_amdgcn_ds_bpermute((lane ^ mask) << 2, __float_as_int(v))); }
; DI void kvnorm_pass(const float* raw, const float* g1, u16* ckv) {
;     ...
;     f32x4 v = *(const f32x4*)(raw + (size_t)row * 256 + lane * 4);
;     float s = v[0] * v[0] + v[1] * v[1] + v[2] * v[2] + v[3] * v[3];
; #pragma unroll
;     for (int o_ = 32; o_ >= 1; o_ >>= 1) s += shx(s, o_, lane);
;     const float r = rsqrtf(s * (1.f / 256.f) + 1e-6f);
;     v = v * g * r;
;     *(u32x2*)(ckv + (size_t)row * 256 + lane * 4) = MK2(pack2(v[0], v[1]), pack2(v[2], v[3]));
;   }
.Lkv_b_go:
	v_pk_mul_f32 v[20:21], v[22:23], v[22:23]
	v_pk_mul_f32 v[18:19], v[24:25], v[24:25]
	v_add_f32_e32 v20, v20, v21
	v_add_f32_e32 v18, v18, v20
	v_add_f32_e32 v18, v19, v18
	v_pk_mul_f32 v[24:25], v[2:3], v[24:25]
	v_pk_mul_f32 v[22:23], v[0:1], v[22:23]
	s_nop 1
	v_add_f32_dpp v18, v18, v18 quad_perm:[1,0,3,2] row_mask:0xf bank_mask:0xf
	s_nop 1
	v_add_f32_dpp v18, v18, v18 quad_perm:[2,3,0,1] row_mask:0xf bank_mask:0xf
	s_nop 1
	v_add_f32_dpp v18, v18, v18 row_half_mirror row_mask:0xf bank_mask:0xf
	s_nop 1
	v_add_f32_dpp v18, v18, v18 row_mirror row_mask:0xf bank_mask:0xf
	s_nop 1
	v_add_f32_dpp v18, v18, v18 row_bcast:15 row_mask:0xa bank_mask:0xf
	s_nop 1
	v_add_f32_dpp v18, v18, v18 row_bcast:31 row_mask:0xc bank_mask:0xf
	s_nop 1
	v_readlane_b32 s0, v18, 63
	s_nop 1
	v_mov_b32_e32 v18, s0
	v_fmamk_f32 v18, v18, 0x3b800000, v211
	v_cmp_gt_f32_e32 vcc, s33, v18
	v_mul_f32_e32 v19, 0x4b800000, v18
	s_nop 0
	v_cndmask_b32_e32 v18, v18, v19, vcc
	v_rsq_f32_e32 v18, v18
	s_nop 0
	v_mul_f32_e32 v19, 0x45800000, v18
	v_cndmask_b32_e32 v18, v18, v19, vcc
	v_pk_mul_f32 v[24:25], v[24:25], v[18:19] op_sel_hi:[1,0]
	v_pk_mul_f32 v[22:23], v[22:23], v[18:19] op_sel_hi:[1,0]
	s_nop 0
	v_cvt_pk_bf16_f32 v22, v22, v23
	v_cvt_pk_bf16_f32 v23, v24, v25
	global_store_dwordx2 v[26:27], v[22:23], off
	s_cmpk_gt_i32 s8, 0x407f
	s_cbranch_scc1 .LBB0_86
	s_branch .Lkv_a
